# attention round top: wait only for the V prefetch (vmcnt 9) instead of store acks; bias row load issued without a wait and its LDS write deferred to before the pre-softmax barrier
# speedup vs baseline: 1.0051x; 1.0018x over previous
; #define LAS __attribute__((address_space(3)))
; __device__ __forceinline__ AttnItem attn_item(int it) {
;     AttnItem a; a.head = it / 768; const int pb = it - a.head * 768, gi = a.head >> 2; a.dsh = gi * 2;
;     const int p0 = pb * 64; int lsh; if (p0 < 32768) { a.seq_base = p0 & ~8191; lsh = 13; } else { a.seq_base = 32768; lsh = 14; }
;     const int lm = lsh - a.dsh; a.m = 1 << lm; const int local = p0 - a.seq_base; a.r = local >> lm; a.i0 = local - (a.r << lm);
;     a.pos0 = a.seq_base + (a.i0 << a.dsh); return a;
; }
; __device__ __forceinline__ void attn_phase(LAS unsigned char* lds, bf16_t* qkv, float* lse, const float* biasT, int G) {
;     ...
;         const int pair = attn_pair(j, cwg, G); if (pair >= 4608) break;
;         const int pairn = (j + 1 < nrounds) ? attn_pair(j + 1, cwg, G) : 4608;
;         const AttnItem a = attn_item(pair * 2 + half);
; #pragma unroll
;         for (int pass = 0; pass < 12; ++pass) *(LAS u32x4*)(vs + (pass * 16 + (ht >> 4)) * VS_PITCH + (ht & 15) * 16) = vreg[pass];
;         if (ht < 129) bs[16 + ht] = biasT[a.head * 132 + ht];
;         __syncthreads();
.LBB0_423:
	s_lshl_b32 s9, s11, 1
	s_add_i32 s9, s9, s94
	s_mul_hi_i32 s0, s9, 0x2aaaaaab
	s_lshr_b32 s1, s0, 31
	s_ashr_i32 s0, s0, 7
	s_add_i32 s10, s0, s1
	s_waitcnt vmcnt(9)
	ds_write_b128 v231, v[8:11]
	ds_write_b128 v231, v[4:7] offset:4608
	ds_write_b128 v231, v[12:15] offset:9216
	ds_write_b128 v231, v[16:19] offset:13824
	ds_write_b128 v231, v[20:23] offset:18432
	ds_write_b128 v231, v[24:27] offset:23040
	ds_write_b128 v231, v[28:31] offset:27648
	ds_write_b128 v231, v[32:35] offset:32256
	ds_write_b128 v231, v[36:39] offset:36864
	ds_write_b128 v231, v[40:43] offset:41472
	ds_write_b128 v231, v[44:47] offset:46080
	ds_write_b128 v231, v[48:51] offset:50688
	s_mov_b64 s[0:1], exec
	v_readlane_b32 s12, v250, 1
	v_readlane_b32 s13, v250, 2
	s_and_b64 s[12:13], s[0:1], s[12:13]
	s_mov_b64 exec, s[12:13]
	s_cbranch_execz .LBB0_425
	s_mul_i32 s11, s10, 0x84
	v_add_u32_e32 v2, s11, v183
	v_readlane_b32 s12, v250, 13
	v_ashrrev_i32_e32 v3, 31, v2
	v_readlane_b32 s13, v250, 14
	s_nop 1
	v_lshl_add_u64 v[2:3], v[2:3], 2, s[12:13]
	global_load_dword v253, v[2:3], off

; #define LAS __attribute__((address_space(3)))
; #define ATT_MMAK(buf, grp) do { _Pragma("unroll") for (int tt = 0; tt < 3; ++tt) { f32x4 acc_ = (f32x4){0.f, 0.f, 0.f, 0.f}; \
;             _Pragma("unroll") for (int ks = 0; ks < 4; ++ks) acc_ = __builtin_amdgcn_mfma_f32_16x16x32_bf16(Kf[buf][tt][ks], Qf[ks], acc_, 0, 0, 0); sa[(grp) * 3 + tt] = acc_; } } while (0)
; template <bool EDGE>
; __device__ __forceinline__ float attn_scores(f32x4 (&sa)[10], const LAS float* bsl, int dl, int kabs0, int m, float scale2) {
;     float mx = -3.0e38f;
; #pragma unroll
;     for (int t9 = 0; t9 < 9; ++t9)
; #pragma unroll
;         for (int j = 0; j < 4; ++j) {
;             bool valid = true;
;             if (t9 == 0) valid = (j + dl >= 0);
;             if (t9 == 8) valid = (j + dl <= 0);
;             if (EDGE) { const int kabs = kabs0 + 16 * t9 + j; valid = valid && (kabs >= 0) && (kabs < m); }
;             float sv = sa[t9][j] * scale2 + bsl[16 * t9 + j];
;             sv = valid ? sv : -1.0e30f;
;             sa[t9][j] = sv; mx = fmaxf(mx, sv);
;         }
;     return mx;
; }
; __device__ __forceinline__ void attn_phase(LAS unsigned char* lds, bf16_t* qkv, float* lse, const float* biasT, int G) {
;     ...
;         ATT_MMAK(1, 1);
;         ATT_MMAK(0, 2);
;     ...
;         sa[9] = (f32x4){0.f, 0.f, 0.f, 0.f};
;         const int kabs0 = a.i0 - 64 + 16 * w4 + 4 * lg;
;         const bool edge = (a.i0 == 0) || (a.i0 + 64 == a.m);
;         float mx = edge ? attn_scores<true>(sa, bsl, dl, kabs0, a.m, scale2) : attn_scores<false>(sa, bsl, dl, kabs0, a.m, scale2);
;         mx = fmaxf(mx, __shfl_xor(mx, 16)); mx = fmaxf(mx, __shfl_xor(mx, 32));
.LBB0_451:
	s_lshl_b32 s14, 1, s11
	s_ashr_i32 s11, s10, 31
	s_waitcnt vmcnt(23)
	v_mfma_f32_16x16x32_bf16 v[56:59], v[56:59], v[96:99], 0
	s_cmp_eq_u32 s30, s31
	s_cselect_b64 s[0:1], -1, 0
	s_add_i32 s16, s13, 64
	s_waitcnt vmcnt(22)
	v_mfma_f32_16x16x32_bf16 v[56:59], v[60:63], v[92:95], v[56:59]
	s_cmp_eq_u32 s16, s14
	s_cselect_b64 s[16:17], -1, 0
	s_or_b64 s[16:17], s[0:1], s[16:17]
	s_waitcnt vmcnt(21)
	v_mfma_f32_16x16x32_bf16 v[56:59], v[64:67], v[88:91], v[56:59]
	s_mov_b64 s[0:1], -1
	s_andn2_b64 vcc, exec, s[16:17]
	s_waitcnt vmcnt(20)
	v_mfma_f32_16x16x32_bf16 v[80:83], v[76:79], v[52:55], v[56:59]
	s_waitcnt vmcnt(19)
	v_mfma_f32_16x16x32_bf16 v[56:59], v[100:103], v[96:99], 0
	s_waitcnt vmcnt(18)
	v_mfma_f32_16x16x32_bf16 v[56:59], v[104:107], v[92:95], v[56:59]
	s_waitcnt vmcnt(17)
	v_mfma_f32_16x16x32_bf16 v[56:59], v[108:111], v[88:91], v[56:59]
	s_waitcnt vmcnt(16)
	v_mfma_f32_16x16x32_bf16 v[76:79], v[112:115], v[52:55], v[56:59]
	s_waitcnt vmcnt(15)
	v_mfma_f32_16x16x32_bf16 v[56:59], v[120:123], v[96:99], 0
	s_waitcnt vmcnt(14)
	v_mfma_f32_16x16x32_bf16 v[56:59], v[124:127], v[92:95], v[56:59]
	s_waitcnt vmcnt(13)
	v_mfma_f32_16x16x32_bf16 v[56:59], v[128:131], v[88:91], v[56:59]
	s_waitcnt vmcnt(12)
	v_mfma_f32_16x16x32_bf16 v[64:67], v[132:135], v[52:55], v[56:59]
	s_waitcnt vmcnt(11)
	v_mfma_f32_16x16x32_bf16 v[56:59], v[136:139], v[96:99], 0
	s_waitcnt vmcnt(10)
	v_mfma_f32_16x16x32_bf16 v[56:59], v[140:143], v[92:95], v[56:59]
	s_waitcnt vmcnt(9)
	v_mfma_f32_16x16x32_bf16 v[56:59], v[144:147], v[88:91], v[56:59]
	s_waitcnt vmcnt(8)
	v_mfma_f32_16x16x32_bf16 v[60:63], v[148:151], v[52:55], v[56:59]
	s_waitcnt vmcnt(7)
	v_mfma_f32_16x16x32_bf16 v[56:59], v[152:155], v[96:99], 0
	s_waitcnt vmcnt(3)
	v_mfma_f32_16x16x32_bf16 v[96:99], v[176:179], v[96:99], 0
	v_mfma_f32_16x16x32_bf16 v[56:59], v[156:159], v[92:95], v[56:59]
	s_waitcnt vmcnt(2)
	v_mfma_f32_16x16x32_bf16 v[92:95], v[172:175], v[92:95], v[96:99]
	v_mfma_f32_16x16x32_bf16 v[56:59], v[160:163], v[88:91], v[56:59]
	s_waitcnt vmcnt(1)
	v_mfma_f32_16x16x32_bf16 v[126:129], v[168:171], v[88:91], v[92:95]
	v_mfma_f32_16x16x32_bf16 v[56:59], v[164:167], v[52:55], v[56:59]
	s_waitcnt vmcnt(0)
	v_mfma_f32_16x16x32_bf16 v[52:55], v[116:119], v[52:55], v[126:129]
	v_readlane_b32 s32, v250, 1
	s_mov_b32 exec_lo, s32
	v_readlane_b32 s32, v250, 2
	s_mov_b32 exec_hi, s32
	ds_write_b32 v185, v253 offset:64
	s_mov_b64 exec, -1
	s_waitcnt lgkmcnt(0)
	s_barrier
	s_cbranch_vccz .LBB0_453
	ds_read2_b32 v[2:3], v218 offset0:16 offset1:17
	s_mov_b32 s0, 0x3e0293ee
	v_readlane_b32 s16, v250, 22
	v_readlane_b32 s17, v250, 23
	s_waitcnt lgkmcnt(0)
	v_pk_fma_f32 v[2:3], v[84:85], s[0:1], v[2:3] op_sel_hi:[1,0,1]
	s_nop 0
	v_cndmask_b32_e64 v0, v212, v3, s[16:17]
	v_readlane_b32 s16, v250, 17
	v_readlane_b32 s17, v250, 18
	s_nop 1
	v_cndmask_b32_e64 v114, v212, v2, s[16:17]
	ds_read2_b32 v[2:3], v218 offset0:18 offset1:19
	v_readlane_b32 s16, v250, 24
	v_readlane_b32 s17, v250, 25
	v_max_f32_e32 v88, 0xff61b1e6, v114
	s_waitcnt lgkmcnt(0)
	v_pk_fma_f32 v[2:3], v[86:87], s[0:1], v[2:3] op_sel_hi:[1,0,1]
	s_nop 0
	v_cndmask_b32_e64 v120, v212, v3, s[16:17]
	v_readlane_b32 s16, v251, 63
	v_readlane_b32 s17, v250, 0
	s_nop 1
	v_cndmask_b32_e64 v115, v212, v2, s[16:17]
	ds_read2_b32 v[2:3], v218 offset0:32 offset1:33
	v_max3_f32 v88, v88, v0, v115
	s_waitcnt lgkmcnt(0)
	v_pk_fma_f32 v[2:3], v[72:73], s[0:1], v[2:3] op_sel_hi:[1,0,1]
	s_nop 0
	v_max3_f32 v90, v88, v120, v2
	ds_read2_b32 v[88:89], v218 offset0:34 offset1:35
	s_waitcnt lgkmcnt(0)
	v_pk_fma_f32 v[88:89], v[74:75], s[0:1], v[88:89] op_sel_hi:[1,0,1]
	s_nop 0
	v_max3_f32 v92, v90, v3, v88
	ds_read2_b32 v[90:91], v218 offset0:48 offset1:49
	s_waitcnt lgkmcnt(0)
	v_pk_fma_f32 v[90:91], v[68:69], s[0:1], v[90:91] op_sel_hi:[1,0,1]
	s_nop 0
	v_max3_f32 v94, v92, v89, v90
	ds_read2_b32 v[92:93], v218 offset0:50 offset1:51
	s_waitcnt lgkmcnt(0)
	v_pk_fma_f32 v[92:93], v[70:71], s[0:1], v[92:93] op_sel_hi:[1,0,1]
	s_nop 0
	v_max3_f32 v96, v94, v91, v92
	ds_read2_b32 v[94:95], v218 offset0:64 offset1:65
	s_waitcnt lgkmcnt(0)
	v_pk_fma_f32 v[94:95], v[80:81], s[0:1], v[94:95] op_sel_hi:[1,0,1]
	s_nop 0
	v_max3_f32 v98, v96, v93, v94
	ds_read2_b32 v[96:97], v218 offset0:66 offset1:67
	s_waitcnt lgkmcnt(0)
	v_pk_fma_f32 v[96:97], v[82:83], s[0:1], v[96:97] op_sel_hi:[1,0,1]
	s_nop 0
	v_max3_f32 v100, v98, v95, v96
	ds_read2_b32 v[98:99], v218 offset0:80 offset1:81
	s_waitcnt lgkmcnt(0)
	v_pk_fma_f32 v[98:99], v[76:77], s[0:1], v[98:99] op_sel_hi:[1,0,1]
	s_nop 0
	v_max3_f32 v102, v100, v97, v98
	ds_read2_b32 v[100:101], v218 offset0:82 offset1:83
	s_waitcnt lgkmcnt(0)
	v_pk_fma_f32 v[100:101], v[78:79], s[0:1], v[100:101] op_sel_hi:[1,0,1]
	s_nop 0
	v_max3_f32 v104, v102, v99, v100
	ds_read2_b32 v[102:103], v218 offset0:96 offset1:97
	s_waitcnt lgkmcnt(0)
	v_pk_fma_f32 v[102:103], v[64:65], s[0:1], v[102:103] op_sel_hi:[1,0,1]
	s_nop 0
	v_max3_f32 v106, v104, v101, v102
	ds_read2_b32 v[104:105], v218 offset0:98 offset1:99
	s_waitcnt lgkmcnt(0)
	v_pk_fma_f32 v[104:105], v[66:67], s[0:1], v[104:105] op_sel_hi:[1,0,1]
	s_nop 0
	v_max3_f32 v108, v106, v103, v104
	ds_read2_b32 v[106:107], v218 offset0:112 offset1:113
	s_waitcnt lgkmcnt(0)
	v_pk_fma_f32 v[106:107], v[60:61], s[0:1], v[106:107] op_sel_hi:[1,0,1]
	s_nop 0
	v_max3_f32 v110, v108, v105, v106
	ds_read2_b32 v[108:109], v218 offset0:114 offset1:115
	s_waitcnt lgkmcnt(0)
	v_pk_fma_f32 v[108:109], v[62:63], s[0:1], v[108:109] op_sel_hi:[1,0,1]
	s_nop 0
	v_max3_f32 v112, v110, v107, v108
	ds_read2_b32 v[110:111], v218 offset0:128 offset1:129
	s_waitcnt lgkmcnt(0)
	v_pk_fma_f32 v[110:111], v[56:57], s[0:1], v[110:111] op_sel_hi:[1,0,1]
	s_nop 0
	v_max3_f32 v116, v112, v109, v110
	ds_read2_b32 v[112:113], v218 offset0:130 offset1:131
	s_waitcnt lgkmcnt(0)
	v_pk_fma_f32 v[112:113], v[58:59], s[0:1], v[112:113] op_sel_hi:[1,0,1]
	s_nop 0
	v_max3_f32 v118, v116, v111, v112
	ds_read2_b32 v[116:117], v218 offset0:144 offset1:145
	s_waitcnt lgkmcnt(0)
	v_pk_fma_f32 v[116:117], v[52:53], s[0:1], v[116:117] op_sel_hi:[1,0,1]
	v_readlane_b32 s0, v250, 11
	v_readlane_b32 s1, v250, 12
	s_nop 1
	v_cndmask_b32_e64 v121, v212, v117, s[0:1]
	ds_read_b32 v117, v218 offset:584
	v_readlane_b32 s0, v250, 9
	v_readlane_b32 s1, v250, 10
	s_waitcnt lgkmcnt(0)
	v_fmac_f32_e32 v117, 0x3e0293ee, v54
	v_cndmask_b32_e64 v122, v212, v116, s[0:1]
	v_max3_f32 v116, v118, v113, v122
	v_cndmask_b32_e64 v123, v212, v117, s[22:23]
	v_max3_f32 v124, v116, v121, v123
	s_mov_b64 s[0:1], 0

; template <bool COOP>
; __global__ void __launch_bounds__(512, 2) fwd_kernel(Params p) {
;     ...
;     }
; }
.LBB0_641:
	s_nop 0
	s_nop 0
	s_nop 0
	s_nop 0
	s_nop 0
	s_nop 0
	s_nop 0
	s_nop 0
	s_nop 0
	s_nop 0
	s_nop 0
	s_nop 0
	s_nop 0
	s_nop 0
	s_nop 0
	s_nop 0
	s_nop 0
	s_nop 0
	s_nop 0
	s_nop 0
	s_nop 0
	s_nop 0
	s_nop 0
	s_nop 0
	s_nop 0
	s_nop 0
	s_nop 0
	s_nop 0
	s_nop 0
	s_nop 0
	s_nop 0
	s_nop 0
	s_nop 0
	s_nop 0
	s_nop 0
	s_nop 0
	s_nop 0
	s_nop 0
	s_nop 0
	s_nop 0
	s_nop 0
	s_nop 0
	s_nop 0
	s_nop 0
	s_nop 0
	s_nop 0
	s_nop 0
	s_nop 0
	s_nop 0
	s_nop 0
	s_nop 0
	s_nop 0
	s_nop 0
	s_nop 0
	s_nop 0
	s_nop 0
	s_nop 0
	s_nop 0
	s_nop 0
	s_nop 0
	s_nop 0
	s_nop 0
	s_nop 0
	s_nop 0
	s_nop 0
	s_nop 0
	s_nop 0
	s_nop 0
	s_nop 0
	s_nop 0
	s_nop 0
	s_nop 0
	s_nop 0
	s_nop 0
	s_nop 0
	s_nop 0
	s_nop 0
	s_nop 0
	s_nop 0
	s_nop 0
	s_nop 0
	s_nop 0
	s_nop 0
	s_nop 0
	s_nop 0
	s_nop 0
	s_nop 0
	s_nop 0
	s_nop 0
	s_nop 0
	s_nop 0
	s_nop 0
	s_nop 0
	s_nop 0
	s_nop 0
	s_nop 0
	s_nop 0
	s_nop 0
	s_nop 0
	s_nop 0
	s_nop 0
	s_nop 0
	s_nop 0
	s_nop 0
	s_nop 0
	s_nop 0
	s_nop 0
	s_nop 0
	s_nop 0
	s_nop 0
	s_nop 0
	s_nop 0
	s_nop 0
	s_nop 0
	s_nop 0
	s_nop 0
	s_nop 0
	s_nop 0
	s_nop 0
	s_nop 0
	s_nop 0
	s_nop 0
	s_nop 0
	s_nop 0
	s_nop 0
	s_nop 0
	s_nop 0
	s_nop 0
	s_nop 0
	s_nop 0
	s_nop 0
	s_nop 0
	s_nop 0
	s_nop 0
	s_nop 0
	s_nop 0
	s_nop 0
	s_nop 0
	s_nop 0
	s_nop 0
	s_nop 0
	s_nop 0
	s_nop 0
	s_nop 0
	s_nop 0
	s_nop 0
	s_nop 0
	s_nop 0
	s_nop 0
	s_nop 0
	s_nop 0
	s_nop 0
	s_nop 0
	s_nop 0
	s_nop 0
	s_nop 0
	s_nop 0
	s_nop 0
	s_nop 0
	s_nop 0
	s_nop 0
	s_nop 0
	s_nop 0
	s_nop 0
	s_nop 0
	s_nop 0
	s_nop 0
	s_nop 0
	s_nop 0
	s_nop 0
	s_nop 0
	s_nop 0
	s_nop 0
	s_nop 0
	s_nop 0
	s_nop 0
	s_nop 0
	s_nop 0
	s_nop 0
	s_nop 0
	s_nop 0
	s_nop 0
	s_nop 0
	s_nop 0
	s_nop 0
	s_nop 0
	s_nop 0
	s_nop 0
	s_nop 0
	s_nop 0
	s_nop 0
	s_nop 0
	s_nop 0
	s_nop 0
	s_nop 0
	s_nop 0
	s_nop 0
	s_nop 0
	s_nop 0
	s_nop 0
	s_nop 0
	s_nop 0
	s_nop 0
	s_nop 0
	s_nop 0
	s_nop 0
	s_nop 0
	s_nop 0
	s_nop 0
	s_nop 0
	s_nop 0
	s_nop 0
	s_nop 0
	s_nop 0
	s_nop 0
	s_nop 0
	s_nop 0
	s_nop 0
	s_nop 0
	s_nop 0
	s_nop 0
	s_nop 0
	s_nop 0
	s_nop 0
	s_nop 0
	s_nop 0
	s_nop 0
	s_nop 0
	s_nop 0
	s_nop 0
	s_nop 0
	s_nop 0
	s_nop 0
	s_nop 0
	s_nop 0
	s_nop 0
	s_nop 0
	s_nop 0
	s_nop 0
	s_nop 0
	s_nop 0
	s_nop 0
	s_nop 0
	s_nop 0
	s_nop 0
	s_nop 0
	s_nop 0
	s_nop 0
	s_nop 0
	s_nop 0
	s_nop 0
	s_nop 0
	s_nop 0
	s_nop 0
	s_nop 0
	s_nop 0
	s_nop 0
	s_nop 0
	s_nop 0
	s_nop 0
	s_nop 0
	s_nop 0
	s_nop 0
	s_nop 0
	s_nop 0
	s_nop 0
	s_nop 0
	s_nop 0
	s_nop 0
	s_nop 0
	s_nop 0
	s_nop 0
	s_nop 0
	s_nop 0
	s_nop 0
	s_nop 0
	s_nop 0
	s_nop 0
	s_nop 0
	s_nop 0
	s_nop 0
	s_nop 0
	s_nop 0
	s_nop 0
	s_nop 0
	s_nop 0
	s_nop 0
	s_nop 0
	s_nop 0
	s_nop 0
	s_nop 0
	s_nop 0
	s_nop 0
	s_nop 0
	s_nop 0
	s_nop 0
	s_nop 0
	s_nop 0
	s_endpgm
